# gate arrays touched (one dword per line, 1/256 share per workgroup) by the waiting waves at the P3-end grid barrier to warm the memory-side cache for P5
# speedup vs baseline: 1.0003x; 1.0003x over previous
.LBB0_1064:
	s_cmp_gt_i32 s73, 4
	s_cselect_b64 s[2:3], -1, 0
	s_and_b64 s[0:1], s[40:41], s[2:3]
	s_andn2_b64 vcc, exec, s[0:1]
	s_cbranch_vccnz .LBB0_1118
	s_waitcnt vmcnt(0)
	s_waitcnt vmcnt(0) lgkmcnt(0)
	s_barrier
	s_mov_b64 s[0:1], exec
	v_readfirstlane_b32 s98, v0
	s_lshr_b32 s98, s98, 6
	s_cmp_eq_u32 s98, 0
	s_cbranch_scc1 .Lmallpf_skip_gates
	s_sub_u32 s98, s98, 1
	s_mul_i32 s98, s98, 192
	v_and_b32_e32 v253, 63, v0
	v_add_u32_e32 v253, s98, v253
	v_readlane_b32 s98, v252, 56
	v_readlane_b32 s99, v252, 57
	s_add_u32 s98, s98, 0x15c00000
	s_addc_u32 s99, s99, 0
	s_mul_i32 s100, s96, 65536
	s_add_u32 s98, s98, s100
	s_addc_u32 s99, s99, 0
	v_mov_b32_e32 v254, v253
	v_min_u32_e32 v254, 0x3ff, v254
	v_lshrrev_b32_e32 v255, 9, v254
	v_and_b32_e32 v254, 0x1ff, v254
	v_lshlrev_b32_e32 v254, 7, v254
	v_lshl_add_u32 v254, v255, 25, v254
	global_load_dword v250, v254, s[98:99]
	v_add_u32_e32 v254, 64, v253
	v_min_u32_e32 v254, 0x3ff, v254
	v_lshrrev_b32_e32 v255, 9, v254
	v_and_b32_e32 v254, 0x1ff, v254
	v_lshlrev_b32_e32 v254, 7, v254
	v_lshl_add_u32 v254, v255, 25, v254
	global_load_dword v250, v254, s[98:99]
	v_add_u32_e32 v254, 128, v253
	v_min_u32_e32 v254, 0x3ff, v254
	v_lshrrev_b32_e32 v255, 9, v254
	v_and_b32_e32 v254, 0x1ff, v254
	v_lshlrev_b32_e32 v254, 7, v254
	v_lshl_add_u32 v254, v255, 25, v254
	global_load_dword v250, v254, s[98:99]
.Lmallpf_skip_gates:
	v_readlane_b32 s4, v252, 37
	v_readlane_b32 s5, v252, 38
	s_and_b64 s[4:5], s[0:1], s[4:5]
	s_mov_b64 exec, s[4:5]
	s_cbranch_execz .LBB0_1117
	s_add_i32 s4, 0, 0x23f20
	v_mov_b32_e32 v1, s4
	s_waitcnt vmcnt(0) expcnt(0) lgkmcnt(0)
	ds_read_b32 v3, v1
	s_add_i32 s4, 0, 0x23f24
	v_mov_b32_e32 v1, s4
	ds_read_b32 v1, v1
	s_waitcnt lgkmcnt(1)
	v_cmp_ne_u32_e32 vcc, 0, v3
	s_cbranch_vccnz .LBB0_1081
	v_readlane_b32 s4, v252, 2
	v_readlane_b32 s5, v252, 3
	s_load_dwordx2 s[8:9], s[4:5], 0x4
	s_add_u32 s4, s88, 0x1000
	s_addc_u32 s5, s89, 0
	s_add_u32 s6, s88, 0x1100
	s_addc_u32 s7, s89, 0
	s_waitcnt lgkmcnt(0)
	s_mul_i32 s18, s8, s84
	s_add_u32 s8, s88, 0x1200
	s_mul_i32 s18, s18, s9
	s_addc_u32 s9, s89, 0
	s_add_u32 s10, s88, 0x1300
	s_addc_u32 s11, s89, 0
	s_mov_b32 s19, 1
	v_mov_b32_e32 v17, 0
	s_branch .LBB0_1069
